# context split-K units of layer 0's out-projection: the two gate-vector loads of the epilogue requested at the top of the unit (on top of the context-attention chunk prefetch)
# baseline (speedup 1.0000x reference)
.LBB0_665:
	s_ashr_i32 s0, s2, 4
	s_addk_i32 s0, 0x80
	s_ashr_i32 s1, s0, 31
	s_and_b32 s16, s2, 1
	s_bfe_u32 s3, s2, 0x30001
	v_mov_b32_e32 v240, s3
	v_lshlrev_b32_e32 v240, 9, v240
	v_mov_b32_e32 v241, 0
	v_lshl_add_u64 v[242:243], v[64:65], 0, v[240:241]
	global_load_dwordx4 v[208:211], v[242:243], off offset:16
	global_load_dwordx4 v[212:215], v[242:243], off
	s_lshl_b64 s[12:13], s[0:1], 18
	s_add_u32 s1, s40, s12
	v_mov_b32_e32 v4, v138
	s_addc_u32 s12, s41, s13
	s_lshl_b32 s13, s16, 10
	s_add_u32 s36, s1, s13
	v_lshrrev_b32_e32 v5, 4, v4
	v_xor_b32_e32 v6, v5, v4
	v_ashrrev_i32_e32 v0, 3, v4
	s_addc_u32 s37, s12, 0
	s_lshl_b32 s1, s3, 18
	v_ashrrev_i32_e32 v1, 31, v0
	v_lshlrev_b32_e32 v6, 4, v6
	s_add_u32 s1, s38, s1
	v_lshlrev_b64 v[0:1], 11, v[0:1]
	v_and_b32_e32 v134, 0x70, v6
	v_lshlrev_b32_e32 v6, 4, v4
	s_addc_u32 s17, s39, 0
	v_lshl_add_u64 v[2:3], s[36:37], 0, v[0:1]
	v_readfirstlane_b32 s57, v6
	v_add_u32_e32 v7, 0x1000, v6
	s_add_u32 s12, s1, s13
	v_lshl_add_u64 v[68:69], v[2:3], 0, v[134:135]
	s_mov_b32 m0, s57
	v_readfirstlane_b32 s56, v7
	v_add_u32_e32 v7, 0x2000, v6
	s_addc_u32 s13, s17, 0
	s_barrier
	global_load_lds_dwordx4 v[68:69], off
	v_lshl_add_u64 v[2:3], v[68:69], 0, s[60:61]
	s_mov_b32 m0, s56
	v_readfirstlane_b32 s43, v7
	v_add_u32_e32 v7, 0x3000, v6
	global_load_lds_dwordx4 v[2:3], off
	v_lshl_add_u64 v[2:3], v[68:69], 0, s[24:25]
	s_mov_b32 m0, s43
	v_readfirstlane_b32 s42, v7
	v_lshl_add_u64 v[0:1], s[12:13], 0, v[0:1]
	global_load_lds_dwordx4 v[2:3], off
	v_lshl_add_u64 v[2:3], v[68:69], 0, s[44:45]
	s_mov_b32 m0, s42
	v_lshl_add_u64 v[70:71], v[0:1], 0, v[134:135]
	v_add_u32_e32 v0, 0x4000, v6
	global_load_lds_dwordx4 v[2:3], off
	v_readfirstlane_b32 s68, v0
	v_add_u32_e32 v2, 0x5000, v6
	s_mov_b32 m0, s68
	v_readfirstlane_b32 s59, v2
	v_add_u32_e32 v2, 0x6000, v6
	global_load_lds_dwordx4 v[70:71], off
	v_lshl_add_u64 v[0:1], v[70:71], 0, s[60:61]
	s_mov_b32 m0, s59
	v_readfirstlane_b32 s58, v2
	v_add_u32_e32 v2, 0x7000, v6
	global_load_lds_dwordx4 v[0:1], off
	v_lshl_add_u64 v[0:1], v[70:71], 0, s[24:25]
	s_mov_b32 m0, s58
	v_readfirstlane_b32 s36, v2
	global_load_lds_dwordx4 v[0:1], off
	v_lshl_add_u64 v[0:1], v[70:71], 0, s[44:45]
	s_mov_b32 m0, s36
	v_bfe_u32 v2, v4, 4, 2
	global_load_lds_dwordx4 v[0:1], off
	v_and_b32_e32 v0, 15, v4
	v_bfe_u32 v1, v4, 1, 3
	v_lshlrev_b32_e32 v8, 7, v0
	v_lshlrev_b32_e32 v0, 7, v4
	v_and_b32_e32 v47, 0x2000, v0
	v_bitop3_b32 v0, v2, v1, 4 bitop3:0x36
	v_add_u32_e32 v2, 0x8000, v6
	v_bitop3_b32 v3, v5, v1, 3 bitop3:0x6c
	v_readfirstlane_b32 s12, v2
	v_add_u32_e32 v2, 0x9000, v6
	v_lshlrev_b32_e32 v48, 4, v0
	v_lshl_add_u64 v[0:1], v[68:69], 0, s[10:11]
	s_mov_b32 m0, s12
	s_mov_b64 s[40:41], 0x10080
	v_readfirstlane_b32 s17, v2
	v_add_u32_e32 v2, 0xa000, v6
	s_waitcnt vmcnt(0)
	s_waitcnt vmcnt(0) lgkmcnt(0)
	s_barrier
	global_load_lds_dwordx4 v[0:1], off
	v_lshl_add_u64 v[0:1], v[68:69], 0, s[40:41]
	s_mov_b32 m0, s17
	v_readfirstlane_b32 s13, v2
	v_add_u32_e32 v2, 0xb000, v6
	global_load_lds_dwordx4 v[0:1], off
	v_lshl_add_u64 v[0:1], v[68:69], 0, s[80:81]
	s_mov_b32 m0, s13
	v_readfirstlane_b32 s18, v2
	v_add_u32_e32 v2, 0xc000, v6
	global_load_lds_dwordx4 v[0:1], off
	v_lshl_add_u64 v[0:1], v[68:69], 0, s[88:89]
	s_mov_b32 m0, s18
	v_readfirstlane_b32 s37, v2
	global_load_lds_dwordx4 v[0:1], off
	v_lshl_add_u64 v[0:1], v[70:71], 0, s[10:11]
	s_mov_b32 m0, s37
	v_add_u32_e32 v2, 0xd000, v6
	global_load_lds_dwordx4 v[0:1], off
	v_lshl_add_u64 v[0:1], v[70:71], 0, s[40:41]
	v_readfirstlane_b32 s40, v2
	v_add_u32_e32 v2, 0xe000, v6
	s_mov_b32 m0, s40
	v_readfirstlane_b32 s41, v2
	v_add_u32_e32 v2, 0xf000, v6
	v_lshlrev_b32_e32 v9, 4, v3
	v_lshlrev_b32_e32 v3, 6, v4
	global_load_lds_dwordx4 v[0:1], off
	v_lshl_add_u64 v[0:1], v[70:71], 0, s[80:81]
	s_mov_b32 m0, s41
	v_readfirstlane_b32 s1, v2
	v_and_b32_e32 v46, 0xffffe000, v3
	global_load_lds_dwordx4 v[0:1], off
	v_lshl_add_u64 v[0:1], v[70:71], 0, s[88:89]
	s_mov_b32 m0, s1
	v_or3_b32 v67, v9, v46, v8
	global_load_lds_dwordx4 v[0:1], off
	v_or3_b32 v74, v9, v47, v8
	ds_read_b128 v[10:13], v67
	ds_read_b128 v[14:17], v67 offset:2048
	ds_read_b128 v[4:7], v67 offset:4096
	ds_read_b128 v[0:3], v67 offset:6144
	ds_read_b128 v[18:21], v74 offset:16384
	ds_read_b128 v[22:25], v74 offset:18432
	ds_read_b128 v[26:29], v74 offset:20480
	ds_read_b128 v[30:33], v74 offset:22528
	s_waitcnt lgkmcnt(0)
	v_mfma_f32_16x16x32_bf16 v[34:37], v[10:13], v[18:21], 0
	v_or3_b32 v75, v48, v46, v8
	v_or3_b32 v76, v48, v47, v8
	s_mov_b32 m0, s57
	v_mfma_f32_16x16x32_bf16 v[78:81], v[14:17], v[18:21], 0
	s_mov_b64 vcc, 0x30100
	s_mov_b64 s[82:83], 0x30180
	s_cmp_eq_u32 s16, 0
	v_mfma_f32_16x16x32_bf16 v[38:41], v[10:13], v[22:25], 0
	v_mfma_f32_16x16x32_bf16 v[42:45], v[10:13], v[26:29], 0
	v_mfma_f32_16x16x32_bf16 v[82:85], v[14:17], v[22:25], 0
	v_mfma_f32_16x16x32_bf16 v[86:89], v[14:17], v[26:29], 0
	v_mfma_f32_16x16x32_bf16 v[90:93], v[4:7], v[18:21], 0
	v_mfma_f32_16x16x32_bf16 v[94:97], v[4:7], v[22:25], 0
	v_mfma_f32_16x16x32_bf16 v[98:101], v[4:7], v[26:29], 0
	v_mfma_f32_16x16x32_bf16 v[102:105], v[4:7], v[30:33], 0
	v_mfma_f32_16x16x32_bf16 v[18:21], v[0:3], v[18:21], 0
	v_mfma_f32_16x16x32_bf16 v[22:25], v[0:3], v[22:25], 0
	v_mfma_f32_16x16x32_bf16 v[26:29], v[0:3], v[26:29], 0
	v_mfma_f32_16x16x32_bf16 v[106:109], v[0:3], v[30:33], 0
	ds_read_b128 v[0:3], v75
	ds_read_b128 v[4:7], v75 offset:2048
	ds_read_b128 v[110:113], v75 offset:4096
	ds_read_b128 v[114:117], v75 offset:6144
	ds_read_b128 v[118:121], v76 offset:16384
	ds_read_b128 v[122:125], v76 offset:18432
	ds_read_b128 v[126:129], v76 offset:20480
	ds_read_b128 v[168:171], v76 offset:22528
	s_waitcnt vmcnt(0)
	v_mfma_f32_16x16x32_bf16 v[10:13], v[10:13], v[30:33], 0
	s_waitcnt vmcnt(0) lgkmcnt(0)
	s_barrier
	v_mfma_f32_16x16x32_bf16 v[14:17], v[14:17], v[30:33], 0
	v_mfma_f32_16x16x32_bf16 v[60:63], v[0:3], v[118:121], v[34:37]
	v_mfma_f32_16x16x32_bf16 v[32:35], v[4:7], v[118:121], v[78:81]
	s_nop 2
	v_lshl_add_u64 v[78:79], v[68:69], 0, s[84:85]
	global_load_lds_dwordx4 v[78:79], off
	v_lshl_add_u64 v[78:79], v[68:69], 0, s[86:87]
	s_mov_b32 m0, s56
	v_mfma_f32_16x16x32_bf16 v[56:59], v[0:3], v[122:125], v[38:41]
	global_load_lds_dwordx4 v[78:79], off
	v_lshl_add_u64 v[78:79], v[68:69], 0, s[96:97]
	s_mov_b32 m0, s43
	v_mfma_f32_16x16x32_bf16 v[52:55], v[0:3], v[126:129], v[42:45]
	global_load_lds_dwordx4 v[78:79], off
	v_lshl_add_u64 v[78:79], v[68:69], 0, vcc
	s_mov_b32 m0, s42
	v_mfma_f32_16x16x32_bf16 v[48:51], v[0:3], v[168:171], v[10:13]
	global_load_lds_dwordx4 v[78:79], off
	v_lshl_add_u64 v[78:79], v[70:71], 0, s[84:85]
	s_mov_b32 m0, s68
	v_mfma_f32_16x16x32_bf16 v[36:39], v[4:7], v[122:125], v[82:85]
	global_load_lds_dwordx4 v[78:79], off
	v_lshl_add_u64 v[78:79], v[70:71], 0, s[86:87]
	s_mov_b32 m0, s59
	v_mfma_f32_16x16x32_bf16 v[40:43], v[4:7], v[126:129], v[86:89]
	global_load_lds_dwordx4 v[78:79], off
	v_lshl_add_u64 v[78:79], v[70:71], 0, s[96:97]
	s_mov_b32 m0, s58
	v_mfma_f32_16x16x32_bf16 v[44:47], v[4:7], v[168:171], v[14:17]
	global_load_lds_dwordx4 v[78:79], off
	v_lshl_add_u64 v[78:79], v[70:71], 0, vcc
	s_mov_b32 m0, s36
	v_mfma_f32_16x16x32_bf16 v[0:3], v[110:113], v[118:121], v[90:93]
	global_load_lds_dwordx4 v[78:79], off
	s_mov_b32 m0, s12
	v_mfma_f32_16x16x32_bf16 v[4:7], v[110:113], v[122:125], v[94:97]
	s_mov_b64 vcc, 0x200
	v_mfma_f32_16x16x32_bf16 v[8:11], v[110:113], v[126:129], v[98:101]
	v_mfma_f32_16x16x32_bf16 v[12:15], v[110:113], v[168:171], v[102:105]
	v_mfma_f32_16x16x32_bf16 v[16:19], v[114:117], v[118:121], v[18:21]
	v_mfma_f32_16x16x32_bf16 v[20:23], v[114:117], v[122:125], v[22:25]
	v_mfma_f32_16x16x32_bf16 v[24:27], v[114:117], v[126:129], v[26:29]
	v_mfma_f32_16x16x32_bf16 v[28:31], v[114:117], v[168:171], v[106:109]
	ds_read_b128 v[78:81], v67 offset:32768
	ds_read_b128 v[82:85], v67 offset:34816
	ds_read_b128 v[86:89], v67 offset:36864
	ds_read_b128 v[90:93], v67 offset:38912
	ds_read_b128 v[94:97], v74 offset:49152
	ds_read_b128 v[98:101], v74 offset:51200
	ds_read_b128 v[102:105], v74 offset:53248
	ds_read_b128 v[106:109], v74 offset:55296
	s_waitcnt lgkmcnt(0)
	v_mfma_f32_16x16x32_bf16 v[60:63], v[78:81], v[94:97], v[60:63]
	v_mfma_f32_16x16x32_bf16 v[56:59], v[78:81], v[98:101], v[56:59]
	v_mfma_f32_16x16x32_bf16 v[52:55], v[78:81], v[102:105], v[52:55]
	v_mfma_f32_16x16x32_bf16 v[48:51], v[78:81], v[106:109], v[48:51]
	v_mfma_f32_16x16x32_bf16 v[32:35], v[82:85], v[94:97], v[32:35]
	v_mfma_f32_16x16x32_bf16 v[36:39], v[82:85], v[98:101], v[36:39]
	v_mfma_f32_16x16x32_bf16 v[40:43], v[82:85], v[102:105], v[40:43]
	v_mfma_f32_16x16x32_bf16 v[44:47], v[82:85], v[106:109], v[44:47]
	v_mfma_f32_16x16x32_bf16 v[0:3], v[86:89], v[94:97], v[0:3]
	v_mfma_f32_16x16x32_bf16 v[4:7], v[86:89], v[98:101], v[4:7]
	v_mfma_f32_16x16x32_bf16 v[8:11], v[86:89], v[102:105], v[8:11]
	v_mfma_f32_16x16x32_bf16 v[12:15], v[86:89], v[106:109], v[12:15]
	v_mfma_f32_16x16x32_bf16 v[16:19], v[90:93], v[94:97], v[16:19]
	v_mfma_f32_16x16x32_bf16 v[20:23], v[90:93], v[98:101], v[20:23]
	v_mfma_f32_16x16x32_bf16 v[24:27], v[90:93], v[102:105], v[24:27]
	v_mfma_f32_16x16x32_bf16 v[28:31], v[90:93], v[106:109], v[28:31]
	ds_read_b128 v[78:81], v75 offset:32768
	ds_read_b128 v[82:85], v75 offset:34816
	ds_read_b128 v[86:89], v75 offset:36864
	ds_read_b128 v[90:93], v75 offset:38912
	ds_read_b128 v[94:97], v76 offset:49152
	ds_read_b128 v[98:101], v76 offset:51200
	ds_read_b128 v[102:105], v76 offset:53248
	ds_read_b128 v[106:109], v76 offset:55296
	s_waitcnt vmcnt(0)
	s_waitcnt vmcnt(0) lgkmcnt(0)
	v_mfma_f32_16x16x32_bf16 v[60:63], v[78:81], v[94:97], v[60:63]
	s_barrier
	v_mfma_f32_16x16x32_bf16 v[56:59], v[78:81], v[98:101], v[56:59]
	v_mfma_f32_16x16x32_bf16 v[52:55], v[78:81], v[102:105], v[52:55]
	v_mfma_f32_16x16x32_bf16 v[48:51], v[78:81], v[106:109], v[48:51]
	v_lshl_add_u64 v[78:79], v[68:69], 0, s[90:91]
	global_load_lds_dwordx4 v[78:79], off
	v_lshl_add_u64 v[78:79], v[68:69], 0, s[22:23]
	s_mov_b32 m0, s17
	v_mfma_f32_16x16x32_bf16 v[32:35], v[82:85], v[94:97], v[32:35]
	global_load_lds_dwordx4 v[78:79], off
	v_lshl_add_u64 v[78:79], v[68:69], 0, s[78:79]
	s_mov_b32 m0, s13
	v_mfma_f32_16x16x32_bf16 v[36:39], v[82:85], v[98:101], v[36:39]
	global_load_lds_dwordx4 v[78:79], off
	v_lshl_add_u64 v[78:79], v[68:69], 0, s[82:83]
	s_mov_b32 m0, s18
	v_mfma_f32_16x16x32_bf16 v[40:43], v[82:85], v[102:105], v[40:43]
	global_load_lds_dwordx4 v[78:79], off
	v_lshl_add_u64 v[78:79], v[70:71], 0, s[90:91]
	s_mov_b32 m0, s37
	v_mfma_f32_16x16x32_bf16 v[44:47], v[82:85], v[106:109], v[44:47]
	global_load_lds_dwordx4 v[78:79], off
	v_lshl_add_u64 v[78:79], v[70:71], 0, s[22:23]
	s_mov_b32 m0, s40
	v_mfma_f32_16x16x32_bf16 v[0:3], v[86:89], v[94:97], v[0:3]
	global_load_lds_dwordx4 v[78:79], off
	v_lshl_add_u64 v[78:79], v[70:71], 0, s[78:79]
	s_mov_b32 m0, s41
	v_mfma_f32_16x16x32_bf16 v[4:7], v[86:89], v[98:101], v[4:7]
	global_load_lds_dwordx4 v[78:79], off
	v_lshl_add_u64 v[78:79], v[70:71], 0, s[82:83]
	s_mov_b32 m0, s1
	v_mfma_f32_16x16x32_bf16 v[8:11], v[86:89], v[102:105], v[8:11]
	global_load_lds_dwordx4 v[78:79], off
	s_mov_b32 m0, s57
	v_mfma_f32_16x16x32_bf16 v[12:15], v[86:89], v[106:109], v[12:15]
	s_mov_b64 s[82:83], 0x30200
	v_mfma_f32_16x16x32_bf16 v[16:19], v[90:93], v[94:97], v[16:19]
	v_mfma_f32_16x16x32_bf16 v[20:23], v[90:93], v[98:101], v[20:23]
	v_mfma_f32_16x16x32_bf16 v[24:27], v[90:93], v[102:105], v[24:27]
	v_mfma_f32_16x16x32_bf16 v[28:31], v[90:93], v[106:109], v[28:31]
	ds_read_b128 v[78:81], v67
	ds_read_b128 v[82:85], v67 offset:2048
	ds_read_b128 v[86:89], v67 offset:4096
	ds_read_b128 v[90:93], v67 offset:6144
	ds_read_b128 v[94:97], v74 offset:16384
	ds_read_b128 v[98:101], v74 offset:18432
	ds_read_b128 v[102:105], v74 offset:20480
	ds_read_b128 v[106:109], v74 offset:22528
	s_waitcnt lgkmcnt(0)
	v_mfma_f32_16x16x32_bf16 v[60:63], v[78:81], v[94:97], v[60:63]
	v_mfma_f32_16x16x32_bf16 v[56:59], v[78:81], v[98:101], v[56:59]
	v_mfma_f32_16x16x32_bf16 v[52:55], v[78:81], v[102:105], v[52:55]
	v_mfma_f32_16x16x32_bf16 v[48:51], v[78:81], v[106:109], v[48:51]
	v_mfma_f32_16x16x32_bf16 v[32:35], v[82:85], v[94:97], v[32:35]
	v_mfma_f32_16x16x32_bf16 v[36:39], v[82:85], v[98:101], v[36:39]
	v_mfma_f32_16x16x32_bf16 v[40:43], v[82:85], v[102:105], v[40:43]
	v_mfma_f32_16x16x32_bf16 v[44:47], v[82:85], v[106:109], v[44:47]
	v_mfma_f32_16x16x32_bf16 v[0:3], v[86:89], v[94:97], v[0:3]
	v_mfma_f32_16x16x32_bf16 v[4:7], v[86:89], v[98:101], v[4:7]
	v_mfma_f32_16x16x32_bf16 v[8:11], v[86:89], v[102:105], v[8:11]
	v_mfma_f32_16x16x32_bf16 v[12:15], v[86:89], v[106:109], v[12:15]
	v_mfma_f32_16x16x32_bf16 v[16:19], v[90:93], v[94:97], v[16:19]
	v_mfma_f32_16x16x32_bf16 v[20:23], v[90:93], v[98:101], v[20:23]
	v_mfma_f32_16x16x32_bf16 v[24:27], v[90:93], v[102:105], v[24:27]
	v_mfma_f32_16x16x32_bf16 v[28:31], v[90:93], v[106:109], v[28:31]
	ds_read_b128 v[78:81], v75
	ds_read_b128 v[82:85], v75 offset:2048
	ds_read_b128 v[86:89], v75 offset:4096
	ds_read_b128 v[90:93], v75 offset:6144
	ds_read_b128 v[94:97], v76 offset:16384
	ds_read_b128 v[98:101], v76 offset:18432
	ds_read_b128 v[102:105], v76 offset:20480
	ds_read_b128 v[106:109], v76 offset:22528
	s_waitcnt vmcnt(0)
	s_waitcnt vmcnt(0) lgkmcnt(0)
	v_mfma_f32_16x16x32_bf16 v[60:63], v[78:81], v[94:97], v[60:63]
	s_barrier
	v_mfma_f32_16x16x32_bf16 v[56:59], v[78:81], v[98:101], v[56:59]
	v_mfma_f32_16x16x32_bf16 v[52:55], v[78:81], v[102:105], v[52:55]
	v_mfma_f32_16x16x32_bf16 v[48:51], v[78:81], v[106:109], v[48:51]
	v_lshl_add_u64 v[78:79], v[68:69], 0, vcc
	global_load_lds_dwordx4 v[78:79], off
	v_lshl_add_u64 v[78:79], v[68:69], 0, s[20:21]
	s_mov_b32 m0, s56
	v_mfma_f32_16x16x32_bf16 v[32:35], v[82:85], v[94:97], v[32:35]
	global_load_lds_dwordx4 v[78:79], off
	v_lshl_add_u64 v[78:79], v[68:69], 0, s[4:5]
	s_mov_b32 m0, s43
	v_mfma_f32_16x16x32_bf16 v[36:39], v[82:85], v[98:101], v[36:39]
	global_load_lds_dwordx4 v[78:79], off
	v_lshl_add_u64 v[78:79], v[68:69], 0, s[82:83]
	s_mov_b32 m0, s42
	v_mfma_f32_16x16x32_bf16 v[40:43], v[82:85], v[102:105], v[40:43]
	global_load_lds_dwordx4 v[78:79], off
	v_lshl_add_u64 v[78:79], v[70:71], 0, vcc
	s_mov_b32 m0, s68
	v_mfma_f32_16x16x32_bf16 v[44:47], v[82:85], v[106:109], v[44:47]
	global_load_lds_dwordx4 v[78:79], off
	v_lshl_add_u64 v[78:79], v[70:71], 0, s[20:21]
	s_mov_b32 m0, s59
	v_mfma_f32_16x16x32_bf16 v[0:3], v[86:89], v[94:97], v[0:3]
	global_load_lds_dwordx4 v[78:79], off
	v_lshl_add_u64 v[78:79], v[70:71], 0, s[4:5]
	s_mov_b32 m0, s58
	v_mfma_f32_16x16x32_bf16 v[4:7], v[86:89], v[98:101], v[4:7]
	global_load_lds_dwordx4 v[78:79], off
	v_lshl_add_u64 v[78:79], v[70:71], 0, s[82:83]
	s_mov_b32 m0, s36
	v_mfma_f32_16x16x32_bf16 v[8:11], v[86:89], v[102:105], v[8:11]
	global_load_lds_dwordx4 v[78:79], off
	s_mov_b32 m0, s12
	v_mfma_f32_16x16x32_bf16 v[12:15], v[86:89], v[106:109], v[12:15]
	s_mov_b64 vcc, 0x10280
	s_mov_b64 s[82:83], 0x30280
	v_mfma_f32_16x16x32_bf16 v[16:19], v[90:93], v[94:97], v[16:19]
	v_mfma_f32_16x16x32_bf16 v[20:23], v[90:93], v[98:101], v[20:23]
	v_mfma_f32_16x16x32_bf16 v[24:27], v[90:93], v[102:105], v[24:27]
	v_mfma_f32_16x16x32_bf16 v[28:31], v[90:93], v[106:109], v[28:31]
	ds_read_b128 v[78:81], v67 offset:32768
	ds_read_b128 v[82:85], v67 offset:34816
	ds_read_b128 v[86:89], v67 offset:36864
	ds_read_b128 v[90:93], v67 offset:38912
	ds_read_b128 v[94:97], v74 offset:49152
	ds_read_b128 v[98:101], v74 offset:51200
	ds_read_b128 v[102:105], v74 offset:53248
	ds_read_b128 v[106:109], v74 offset:55296
	s_waitcnt lgkmcnt(0)
	v_mfma_f32_16x16x32_bf16 v[60:63], v[78:81], v[94:97], v[60:63]
	v_mfma_f32_16x16x32_bf16 v[56:59], v[78:81], v[98:101], v[56:59]
	v_mfma_f32_16x16x32_bf16 v[52:55], v[78:81], v[102:105], v[52:55]
	v_mfma_f32_16x16x32_bf16 v[48:51], v[78:81], v[106:109], v[48:51]
	v_mfma_f32_16x16x32_bf16 v[32:35], v[82:85], v[94:97], v[32:35]
	v_mfma_f32_16x16x32_bf16 v[36:39], v[82:85], v[98:101], v[36:39]
	v_mfma_f32_16x16x32_bf16 v[40:43], v[82:85], v[102:105], v[40:43]
	v_mfma_f32_16x16x32_bf16 v[44:47], v[82:85], v[106:109], v[44:47]
	v_mfma_f32_16x16x32_bf16 v[0:3], v[86:89], v[94:97], v[0:3]
	v_mfma_f32_16x16x32_bf16 v[4:7], v[86:89], v[98:101], v[4:7]
	v_mfma_f32_16x16x32_bf16 v[8:11], v[86:89], v[102:105], v[8:11]
	v_mfma_f32_16x16x32_bf16 v[12:15], v[86:89], v[106:109], v[12:15]
	v_mfma_f32_16x16x32_bf16 v[16:19], v[90:93], v[94:97], v[16:19]
	v_mfma_f32_16x16x32_bf16 v[20:23], v[90:93], v[98:101], v[20:23]
	v_mfma_f32_16x16x32_bf16 v[24:27], v[90:93], v[102:105], v[24:27]
	v_mfma_f32_16x16x32_bf16 v[28:31], v[90:93], v[106:109], v[28:31]
	ds_read_b128 v[78:81], v75 offset:32768
	ds_read_b128 v[82:85], v75 offset:34816
	ds_read_b128 v[86:89], v75 offset:36864
	ds_read_b128 v[90:93], v75 offset:38912
	ds_read_b128 v[94:97], v76 offset:49152
	ds_read_b128 v[98:101], v76 offset:51200
	ds_read_b128 v[102:105], v76 offset:53248
	ds_read_b128 v[106:109], v76 offset:55296
	s_waitcnt vmcnt(0)
	s_waitcnt vmcnt(0) lgkmcnt(0)
	v_mfma_f32_16x16x32_bf16 v[60:63], v[78:81], v[94:97], v[60:63]
	s_barrier
	v_mfma_f32_16x16x32_bf16 v[56:59], v[78:81], v[98:101], v[56:59]
	v_mfma_f32_16x16x32_bf16 v[52:55], v[78:81], v[102:105], v[52:55]
	v_mfma_f32_16x16x32_bf16 v[48:51], v[78:81], v[106:109], v[48:51]
	v_lshl_add_u64 v[78:79], v[68:69], 0, s[52:53]
	global_load_lds_dwordx4 v[78:79], off
	v_lshl_add_u64 v[78:79], v[68:69], 0, vcc
	s_mov_b32 m0, s17
	v_mfma_f32_16x16x32_bf16 v[32:35], v[82:85], v[94:97], v[32:35]
	global_load_lds_dwordx4 v[78:79], off
	v_lshl_add_u64 v[78:79], v[68:69], 0, s[62:63]
	s_mov_b32 m0, s13
	v_mfma_f32_16x16x32_bf16 v[36:39], v[82:85], v[98:101], v[36:39]
	global_load_lds_dwordx4 v[78:79], off
	v_lshl_add_u64 v[78:79], v[68:69], 0, s[82:83]
	s_mov_b32 m0, s18
	v_mfma_f32_16x16x32_bf16 v[40:43], v[82:85], v[102:105], v[40:43]
	global_load_lds_dwordx4 v[78:79], off
	v_lshl_add_u64 v[78:79], v[70:71], 0, s[52:53]
	s_mov_b32 m0, s37
	v_mfma_f32_16x16x32_bf16 v[44:47], v[82:85], v[106:109], v[44:47]
	global_load_lds_dwordx4 v[78:79], off
	v_lshl_add_u64 v[78:79], v[70:71], 0, vcc
	s_mov_b32 m0, s40
	v_mfma_f32_16x16x32_bf16 v[0:3], v[86:89], v[94:97], v[0:3]
	global_load_lds_dwordx4 v[78:79], off
	v_lshl_add_u64 v[78:79], v[70:71], 0, s[62:63]
	s_mov_b32 m0, s41
	v_mfma_f32_16x16x32_bf16 v[4:7], v[86:89], v[98:101], v[4:7]
	global_load_lds_dwordx4 v[78:79], off
	v_lshl_add_u64 v[78:79], v[70:71], 0, s[82:83]
	s_mov_b32 m0, s1
	v_mfma_f32_16x16x32_bf16 v[8:11], v[86:89], v[102:105], v[8:11]
	global_load_lds_dwordx4 v[78:79], off
	s_mov_b32 m0, s57
	v_mfma_f32_16x16x32_bf16 v[12:15], v[86:89], v[106:109], v[12:15]
	s_mov_b64 vcc, 0x10300
	s_mov_b64 s[82:83], 0x30300
	s_mov_b32 s57, 0xfffffc0
	v_mfma_f32_16x16x32_bf16 v[16:19], v[90:93], v[94:97], v[16:19]
	v_mfma_f32_16x16x32_bf16 v[20:23], v[90:93], v[98:101], v[20:23]
	v_mfma_f32_16x16x32_bf16 v[24:27], v[90:93], v[102:105], v[24:27]
	v_mfma_f32_16x16x32_bf16 v[28:31], v[90:93], v[106:109], v[28:31]
	ds_read_b128 v[78:81], v67
	ds_read_b128 v[82:85], v67 offset:2048
	ds_read_b128 v[86:89], v67 offset:4096
	ds_read_b128 v[90:93], v67 offset:6144
	ds_read_b128 v[94:97], v74 offset:16384
	ds_read_b128 v[98:101], v74 offset:18432
	ds_read_b128 v[102:105], v74 offset:20480
	ds_read_b128 v[106:109], v74 offset:22528
	s_waitcnt lgkmcnt(0)
	v_mfma_f32_16x16x32_bf16 v[60:63], v[78:81], v[94:97], v[60:63]
	v_mfma_f32_16x16x32_bf16 v[56:59], v[78:81], v[98:101], v[56:59]
	v_mfma_f32_16x16x32_bf16 v[52:55], v[78:81], v[102:105], v[52:55]
	v_mfma_f32_16x16x32_bf16 v[48:51], v[78:81], v[106:109], v[48:51]
	v_mfma_f32_16x16x32_bf16 v[32:35], v[82:85], v[94:97], v[32:35]
	v_mfma_f32_16x16x32_bf16 v[36:39], v[82:85], v[98:101], v[36:39]
	v_mfma_f32_16x16x32_bf16 v[40:43], v[82:85], v[102:105], v[40:43]
	v_mfma_f32_16x16x32_bf16 v[44:47], v[82:85], v[106:109], v[44:47]
	v_mfma_f32_16x16x32_bf16 v[0:3], v[86:89], v[94:97], v[0:3]
	v_mfma_f32_16x16x32_bf16 v[4:7], v[86:89], v[98:101], v[4:7]
	v_mfma_f32_16x16x32_bf16 v[8:11], v[86:89], v[102:105], v[8:11]
	v_mfma_f32_16x16x32_bf16 v[12:15], v[86:89], v[106:109], v[12:15]
	v_mfma_f32_16x16x32_bf16 v[16:19], v[90:93], v[94:97], v[16:19]
	v_mfma_f32_16x16x32_bf16 v[20:23], v[90:93], v[98:101], v[20:23]
	v_mfma_f32_16x16x32_bf16 v[24:27], v[90:93], v[102:105], v[24:27]
	v_mfma_f32_16x16x32_bf16 v[28:31], v[90:93], v[106:109], v[28:31]
	ds_read_b128 v[78:81], v75
	ds_read_b128 v[82:85], v75 offset:2048
	ds_read_b128 v[86:89], v75 offset:4096
	ds_read_b128 v[90:93], v75 offset:6144
	ds_read_b128 v[94:97], v76 offset:16384
	ds_read_b128 v[98:101], v76 offset:18432
	ds_read_b128 v[102:105], v76 offset:20480
	ds_read_b128 v[106:109], v76 offset:22528
	s_waitcnt vmcnt(0)
	s_waitcnt vmcnt(0) lgkmcnt(0)
	v_mfma_f32_16x16x32_bf16 v[60:63], v[78:81], v[94:97], v[60:63]
	s_barrier
	v_mfma_f32_16x16x32_bf16 v[56:59], v[78:81], v[98:101], v[56:59]
	v_mfma_f32_16x16x32_bf16 v[52:55], v[78:81], v[102:105], v[52:55]
	v_mfma_f32_16x16x32_bf16 v[48:51], v[78:81], v[106:109], v[48:51]
	v_lshl_add_u64 v[78:79], v[68:69], 0, s[50:51]
	global_load_lds_dwordx4 v[78:79], off
	v_lshl_add_u64 v[78:79], v[68:69], 0, vcc
	s_mov_b32 m0, s56
	v_mfma_f32_16x16x32_bf16 v[32:35], v[82:85], v[94:97], v[32:35]
	global_load_lds_dwordx4 v[78:79], off
	v_lshl_add_u64 v[78:79], v[68:69], 0, s[70:71]
	s_mov_b32 m0, s43
	v_mfma_f32_16x16x32_bf16 v[36:39], v[82:85], v[98:101], v[36:39]
	global_load_lds_dwordx4 v[78:79], off
	v_lshl_add_u64 v[78:79], v[68:69], 0, s[82:83]
	s_mov_b32 m0, s42
	v_mfma_f32_16x16x32_bf16 v[40:43], v[82:85], v[102:105], v[40:43]
	global_load_lds_dwordx4 v[78:79], off
	v_lshl_add_u64 v[78:79], v[70:71], 0, s[50:51]
	s_mov_b32 m0, s68
	v_mfma_f32_16x16x32_bf16 v[44:47], v[82:85], v[106:109], v[44:47]
	global_load_lds_dwordx4 v[78:79], off
	v_lshl_add_u64 v[78:79], v[70:71], 0, vcc
	s_mov_b32 m0, s59
	v_mfma_f32_16x16x32_bf16 v[0:3], v[86:89], v[94:97], v[0:3]
	global_load_lds_dwordx4 v[78:79], off
	v_lshl_add_u64 v[78:79], v[70:71], 0, s[70:71]
	s_mov_b32 m0, s58
	v_mfma_f32_16x16x32_bf16 v[4:7], v[86:89], v[98:101], v[4:7]
	global_load_lds_dwordx4 v[78:79], off
	v_lshl_add_u64 v[78:79], v[70:71], 0, s[82:83]
	s_mov_b32 m0, s36
	v_mfma_f32_16x16x32_bf16 v[8:11], v[86:89], v[102:105], v[8:11]
	global_load_lds_dwordx4 v[78:79], off
	s_mov_b32 m0, s12
	v_mfma_f32_16x16x32_bf16 v[12:15], v[86:89], v[106:109], v[12:15]
	s_mov_b64 s[58:59], 0x10380
	s_mov_b32 s42, 0x10000
	v_mfma_f32_16x16x32_bf16 v[16:19], v[90:93], v[94:97], v[16:19]
	v_mfma_f32_16x16x32_bf16 v[20:23], v[90:93], v[98:101], v[20:23]
	v_mfma_f32_16x16x32_bf16 v[24:27], v[90:93], v[102:105], v[24:27]
	v_mfma_f32_16x16x32_bf16 v[28:31], v[90:93], v[106:109], v[28:31]
	ds_read_b128 v[78:81], v67 offset:32768
	ds_read_b128 v[82:85], v67 offset:34816
	ds_read_b128 v[86:89], v67 offset:36864
	ds_read_b128 v[90:93], v67 offset:38912
	ds_read_b128 v[94:97], v74 offset:49152
	ds_read_b128 v[98:101], v74 offset:51200
	ds_read_b128 v[102:105], v74 offset:53248
	ds_read_b128 v[106:109], v74 offset:55296
	s_waitcnt lgkmcnt(0)
	v_mfma_f32_16x16x32_bf16 v[60:63], v[78:81], v[94:97], v[60:63]
	v_mfma_f32_16x16x32_bf16 v[56:59], v[78:81], v[98:101], v[56:59]
	v_mfma_f32_16x16x32_bf16 v[52:55], v[78:81], v[102:105], v[52:55]
	v_mfma_f32_16x16x32_bf16 v[48:51], v[78:81], v[106:109], v[48:51]
	v_mfma_f32_16x16x32_bf16 v[32:35], v[82:85], v[94:97], v[32:35]
	v_mfma_f32_16x16x32_bf16 v[36:39], v[82:85], v[98:101], v[36:39]
	v_mfma_f32_16x16x32_bf16 v[40:43], v[82:85], v[102:105], v[40:43]
	v_mfma_f32_16x16x32_bf16 v[44:47], v[82:85], v[106:109], v[44:47]
	v_mfma_f32_16x16x32_bf16 v[0:3], v[86:89], v[94:97], v[0:3]
	v_mfma_f32_16x16x32_bf16 v[4:7], v[86:89], v[98:101], v[4:7]
	v_mfma_f32_16x16x32_bf16 v[8:11], v[86:89], v[102:105], v[8:11]
	v_mfma_f32_16x16x32_bf16 v[12:15], v[86:89], v[106:109], v[12:15]
	v_mfma_f32_16x16x32_bf16 v[78:81], v[90:93], v[94:97], v[16:19]
	v_mfma_f32_16x16x32_bf16 v[82:85], v[90:93], v[98:101], v[20:23]
	v_mfma_f32_16x16x32_bf16 v[86:89], v[90:93], v[102:105], v[24:27]
	v_mfma_f32_16x16x32_bf16 v[90:93], v[90:93], v[106:109], v[28:31]
	ds_read_b128 v[16:19], v75 offset:32768
	ds_read_b128 v[20:23], v75 offset:34816
	s_nop 0
	ds_read_b128 v[28:31], v75 offset:36864
	ds_read_b128 v[94:97], v75 offset:38912
	ds_read_b128 v[98:101], v76 offset:49152
	ds_read_b128 v[102:105], v76 offset:51200
	ds_read_b128 v[106:109], v76 offset:53248
	ds_read_b128 v[110:113], v76 offset:55296
	s_waitcnt vmcnt(0)
	s_waitcnt vmcnt(0) lgkmcnt(0)
	v_mfma_f32_16x16x32_bf16 v[60:63], v[16:19], v[98:101], v[60:63]
	s_barrier
	v_mfma_f32_16x16x32_bf16 v[56:59], v[16:19], v[102:105], v[56:59]
	v_mfma_f32_16x16x32_bf16 v[52:55], v[16:19], v[106:109], v[52:55]
	v_mfma_f32_16x16x32_bf16 v[48:51], v[16:19], v[110:113], v[48:51]
	v_mfma_f32_16x16x32_bf16 v[16:19], v[28:31], v[98:101], v[0:3]
	v_mfma_f32_16x16x32_bf16 v[0:3], v[94:97], v[98:101], v[78:81]
	s_nop 2
	v_lshl_add_u64 v[78:79], v[68:69], 0, s[8:9]
	global_load_lds_dwordx4 v[78:79], off
	v_lshl_add_u64 v[78:79], v[68:69], 0, s[58:59]
	s_mov_b32 m0, s17
	v_mfma_f32_16x16x32_bf16 v[32:35], v[20:23], v[98:101], v[32:35]
	global_load_lds_dwordx4 v[78:79], off
	v_lshl_add_u64 v[78:79], v[68:69], 0, s[76:77]
	s_mov_b32 m0, s13
	s_mov_b64 s[12:13], 0x30380
	global_load_lds_dwordx4 v[78:79], off
	v_lshl_add_u64 v[68:69], v[68:69], 0, s[12:13]
	s_mov_b32 m0, s18
	v_mfma_f32_16x16x32_bf16 v[36:39], v[20:23], v[102:105], v[36:39]
	global_load_lds_dwordx4 v[68:69], off
	v_lshl_add_u64 v[68:69], v[70:71], 0, s[8:9]
	s_mov_b32 m0, s37
	v_mfma_f32_16x16x32_bf16 v[40:43], v[20:23], v[106:109], v[40:43]
	global_load_lds_dwordx4 v[68:69], off
	v_lshl_add_u64 v[68:69], v[70:71], 0, s[58:59]
	s_mov_b32 m0, s40
	v_mfma_f32_16x16x32_bf16 v[44:47], v[20:23], v[110:113], v[44:47]
	global_load_lds_dwordx4 v[68:69], off
	v_lshl_add_u64 v[68:69], v[70:71], 0, s[76:77]
	s_mov_b32 m0, s41
	v_mfma_f32_16x16x32_bf16 v[20:23], v[28:31], v[102:105], v[4:7]
	global_load_lds_dwordx4 v[68:69], off
	v_lshl_add_u64 v[68:69], v[70:71], 0, s[12:13]
	s_mov_b32 m0, s1
	v_mfma_f32_16x16x32_bf16 v[24:27], v[28:31], v[106:109], v[8:11]
	global_load_lds_dwordx4 v[68:69], off
	s_mov_b32 s1, 0xa500000
	v_mfma_f32_16x16x32_bf16 v[28:31], v[28:31], v[110:113], v[12:15]
	s_cselect_b32 s1, s1, 0xc700000
	s_add_u32 s1, s94, s1
	s_addc_u32 s12, s95, 0
	v_mfma_f32_16x16x32_bf16 v[4:7], v[94:97], v[102:105], v[82:85]
	s_lshl_b32 s18, s3, 9
	s_mov_b32 s13, 0x30000
	s_mov_b32 s3, 0x40000
	v_mfma_f32_16x16x32_bf16 v[8:11], v[94:97], v[106:109], v[86:89]
	v_readlane_b32 s40, v205, 16
	v_readlane_b32 s41, v205, 17
	v_mfma_f32_16x16x32_bf16 v[12:15], v[94:97], v[110:113], v[90:93]
	ds_read_b128 v[68:71], v67
	ds_read_b128 v[78:81], v67 offset:2048
	ds_read_b128 v[82:85], v67 offset:4096
	ds_read_b128 v[86:89], v67 offset:6144
	ds_read_b128 v[90:93], v74 offset:16384
	ds_read_b128 v[94:97], v74 offset:18432
	ds_read_b128 v[98:101], v74 offset:20480
	ds_read_b128 v[102:105], v74 offset:22528
	s_waitcnt lgkmcnt(0)
	v_mfma_f32_16x16x32_bf16 v[60:63], v[68:71], v[90:93], v[60:63]
	v_mfma_f32_16x16x32_bf16 v[56:59], v[68:71], v[94:97], v[56:59]
	v_mfma_f32_16x16x32_bf16 v[52:55], v[68:71], v[98:101], v[52:55]
	v_mfma_f32_16x16x32_bf16 v[48:51], v[68:71], v[102:105], v[48:51]
	v_mfma_f32_16x16x32_bf16 v[32:35], v[78:81], v[90:93], v[32:35]
	v_mfma_f32_16x16x32_bf16 v[36:39], v[78:81], v[94:97], v[36:39]
	v_mfma_f32_16x16x32_bf16 v[40:43], v[78:81], v[98:101], v[40:43]
	v_mfma_f32_16x16x32_bf16 v[44:47], v[78:81], v[102:105], v[44:47]
	v_mfma_f32_16x16x32_bf16 v[16:19], v[82:85], v[90:93], v[16:19]
	v_mfma_f32_16x16x32_bf16 v[20:23], v[82:85], v[94:97], v[20:23]
	v_mfma_f32_16x16x32_bf16 v[24:27], v[82:85], v[98:101], v[24:27]
	v_mfma_f32_16x16x32_bf16 v[28:31], v[82:85], v[102:105], v[28:31]
	v_mfma_f32_16x16x32_bf16 v[0:3], v[86:89], v[90:93], v[0:3]
	v_mfma_f32_16x16x32_bf16 v[4:7], v[86:89], v[94:97], v[4:7]
	v_mfma_f32_16x16x32_bf16 v[8:11], v[86:89], v[98:101], v[8:11]
	v_mfma_f32_16x16x32_bf16 v[12:15], v[86:89], v[102:105], v[12:15]
	ds_read_b128 v[68:71], v75
	ds_read_b128 v[78:81], v75 offset:2048
	ds_read_b128 v[82:85], v75 offset:4096
	ds_read_b128 v[86:89], v75 offset:6144
	ds_read_b128 v[90:93], v76 offset:16384
	ds_read_b128 v[94:97], v76 offset:18432
	ds_read_b128 v[98:101], v76 offset:20480
	ds_read_b128 v[102:105], v76 offset:22528
	s_waitcnt vmcnt(0)
	s_waitcnt vmcnt(0) lgkmcnt(0)
	v_mfma_f32_16x16x32_bf16 v[60:63], v[68:71], v[90:93], v[60:63]
	s_barrier
	v_mfma_f32_16x16x32_bf16 v[56:59], v[68:71], v[94:97], v[56:59]
	v_mfma_f32_16x16x32_bf16 v[52:55], v[68:71], v[98:101], v[52:55]
	v_mfma_f32_16x16x32_bf16 v[48:51], v[68:71], v[102:105], v[48:51]
	v_mfma_f32_16x16x32_bf16 v[32:35], v[78:81], v[90:93], v[32:35]
	v_mfma_f32_16x16x32_bf16 v[36:39], v[78:81], v[94:97], v[36:39]
	v_mfma_f32_16x16x32_bf16 v[40:43], v[78:81], v[98:101], v[40:43]
	v_mfma_f32_16x16x32_bf16 v[44:47], v[78:81], v[102:105], v[44:47]
	v_mfma_f32_16x16x32_bf16 v[16:19], v[82:85], v[90:93], v[16:19]
	v_mfma_f32_16x16x32_bf16 v[20:23], v[82:85], v[94:97], v[20:23]
	v_mfma_f32_16x16x32_bf16 v[24:27], v[82:85], v[98:101], v[24:27]
	v_mfma_f32_16x16x32_bf16 v[28:31], v[82:85], v[102:105], v[28:31]
	v_mfma_f32_16x16x32_bf16 v[0:3], v[86:89], v[90:93], v[0:3]
	v_mfma_f32_16x16x32_bf16 v[4:7], v[86:89], v[94:97], v[4:7]
	v_mfma_f32_16x16x32_bf16 v[8:11], v[86:89], v[98:101], v[8:11]
	v_mfma_f32_16x16x32_bf16 v[12:15], v[86:89], v[102:105], v[12:15]
	ds_read_b128 v[68:71], v67 offset:32768
	ds_read_b128 v[78:81], v67 offset:34816
	ds_read_b128 v[82:85], v67 offset:36864
	ds_read_b128 v[86:89], v67 offset:38912
	ds_read_b128 v[90:93], v74 offset:49152
	ds_read_b128 v[94:97], v74 offset:51200
	ds_read_b128 v[98:101], v74 offset:53248
	ds_read_b128 v[102:105], v74 offset:55296
	v_mov_b32_e32 v67, v138
	s_waitcnt lgkmcnt(3)
	v_mfma_f32_16x16x32_bf16 v[60:63], v[68:71], v[90:93], v[60:63]
	s_waitcnt lgkmcnt(2)
	v_mfma_f32_16x16x32_bf16 v[56:59], v[68:71], v[94:97], v[56:59]
	s_waitcnt lgkmcnt(1)
	v_mfma_f32_16x16x32_bf16 v[52:55], v[68:71], v[98:101], v[52:55]
	s_waitcnt lgkmcnt(0)
	v_mfma_f32_16x16x32_bf16 v[48:51], v[68:71], v[102:105], v[48:51]
	v_mfma_f32_16x16x32_bf16 v[32:35], v[78:81], v[90:93], v[32:35]
	v_mfma_f32_16x16x32_bf16 v[36:39], v[78:81], v[94:97], v[36:39]
	v_mfma_f32_16x16x32_bf16 v[40:43], v[78:81], v[98:101], v[40:43]
	v_mfma_f32_16x16x32_bf16 v[44:47], v[78:81], v[102:105], v[44:47]
	v_mfma_f32_16x16x32_bf16 v[16:19], v[82:85], v[90:93], v[16:19]
	v_mfma_f32_16x16x32_bf16 v[20:23], v[82:85], v[94:97], v[20:23]
	v_mfma_f32_16x16x32_bf16 v[24:27], v[82:85], v[98:101], v[24:27]
	v_mfma_f32_16x16x32_bf16 v[28:31], v[82:85], v[102:105], v[28:31]
	v_mfma_f32_16x16x32_bf16 v[0:3], v[86:89], v[90:93], v[0:3]
	v_mfma_f32_16x16x32_bf16 v[4:7], v[86:89], v[94:97], v[4:7]
	v_mfma_f32_16x16x32_bf16 v[8:11], v[86:89], v[98:101], v[8:11]
	v_mfma_f32_16x16x32_bf16 v[12:15], v[86:89], v[102:105], v[12:15]
	ds_read_b128 v[68:71], v75 offset:32768
	ds_read_b128 v[78:81], v75 offset:34816
	ds_read_b128 v[82:85], v75 offset:36864
	ds_read_b128 v[86:89], v75 offset:38912
	ds_read_b128 v[90:93], v76 offset:49152
	ds_read_b128 v[94:97], v76 offset:51200
	ds_read_b128 v[98:101], v76 offset:53248
	ds_read_b128 v[74:77], v76 offset:55296
	s_waitcnt lgkmcnt(0)
	s_barrier
	v_mfma_f32_16x16x32_bf16 v[60:63], v[68:71], v[90:93], v[60:63]
	v_mfma_f32_16x16x32_bf16 v[56:59], v[68:71], v[94:97], v[56:59]
	v_mfma_f32_16x16x32_bf16 v[52:55], v[68:71], v[98:101], v[52:55]
	v_mfma_f32_16x16x32_bf16 v[48:51], v[68:71], v[74:77], v[48:51]
	v_mov_b32_e32 v68, v138
	v_and_b32_e32 v69, 15, v67
	v_lshrrev_b32_e32 v67, 2, v67
	v_and_b32_e32 v67, 12, v67
	v_lshrrev_b32_e32 v70, 1, v68
	v_and_or_b32 v67, v70, s57, v67
	v_mfma_f32_16x16x32_bf16 v[32:35], v[78:81], v[90:93], v[32:35]
	v_and_or_b32 v68, v68, 64, v69
	v_mul_lo_u32 v67, v67, s75
	v_lshl_add_u32 v67, v68, 2, v67
	v_mfma_f32_16x16x32_bf16 v[36:39], v[78:81], v[94:97], v[36:39]
	ds_write2_b32 v67, v60, v56 offset1:16
	ds_write2_b32 v67, v61, v57 offset0:132 offset1:148
	v_add_u32_e32 v56, 0x400, v67
	ds_write2_b32 v56, v62, v58 offset0:8 offset1:24
	ds_write2_b32 v56, v63, v59 offset0:140 offset1:156
	ds_write2_b32 v67, v52, v48 offset0:32 offset1:48
	ds_write2_b32 v67, v53, v49 offset0:164 offset1:180
	ds_write2_b32 v56, v54, v50 offset0:40 offset1:56
	ds_write2_b32 v56, v55, v51 offset0:172 offset1:188
	v_mfma_f32_16x16x32_bf16 v[16:19], v[82:85], v[90:93], v[16:19]
	v_add_u32_e32 v48, 0x2000, v67
	ds_write2_b32 v48, v32, v36 offset0:64 offset1:80
	ds_write2_b32 v48, v33, v37 offset0:196 offset1:212
	v_add_u32_e32 v32, 0x2400, v67
	v_mfma_f32_16x16x32_bf16 v[20:23], v[82:85], v[94:97], v[20:23]
	v_mfma_f32_16x16x32_bf16 v[40:43], v[78:81], v[98:101], v[40:43]
	v_mfma_f32_16x16x32_bf16 v[44:47], v[78:81], v[74:77], v[44:47]
	ds_write2_b32 v32, v34, v38 offset0:72 offset1:88
	ds_write2_b32 v32, v35, v39 offset0:204 offset1:220
	s_nop 5
	ds_write2_b32 v48, v40, v44 offset0:96 offset1:112
	ds_write2_b32 v48, v41, v45 offset0:228 offset1:244
	ds_write2_b32 v32, v42, v46 offset0:104 offset1:120
	ds_write2_b32 v32, v43, v47 offset0:236 offset1:252
	v_add_u32_e32 v32, 0x4000, v67
	v_mfma_f32_16x16x32_bf16 v[24:27], v[82:85], v[98:101], v[24:27]
	ds_write2_b32 v32, v16, v20 offset0:128 offset1:144
	v_add_u32_e32 v16, 0x4400, v67
	ds_write2_b32 v16, v17, v21 offset0:4 offset1:20
	ds_write2_b32 v16, v18, v22 offset0:136 offset1:152
	v_mfma_f32_16x16x32_bf16 v[28:31], v[82:85], v[74:77], v[28:31]
	v_add_u32_e32 v17, 0x4800, v67
	ds_write2_b32 v17, v19, v23 offset0:12 offset1:28
	s_nop 5
	ds_write2_b32 v32, v24, v28 offset0:160 offset1:176
	ds_write2_b32 v16, v25, v29 offset0:36 offset1:52
	ds_write2_b32 v16, v26, v30 offset0:168 offset1:184
	ds_write2_b32 v17, v27, v31 offset0:44 offset1:60
	v_mfma_f32_16x16x32_bf16 v[0:3], v[86:89], v[90:93], v[0:3]
	v_add_u32_e32 v16, 0x6000, v67
	v_mfma_f32_16x16x32_bf16 v[4:7], v[86:89], v[94:97], v[4:7]
	v_mfma_f32_16x16x32_bf16 v[8:11], v[86:89], v[98:101], v[8:11]
	v_mfma_f32_16x16x32_bf16 v[12:15], v[86:89], v[74:77], v[12:15]
	s_nop 5
	ds_write2_b32 v16, v0, v4 offset0:192 offset1:208
	v_add_u32_e32 v0, 0x6400, v67
	ds_write2_b32 v0, v1, v5 offset0:68 offset1:84
	ds_write2_b32 v0, v2, v6 offset0:200 offset1:216
	v_add_u32_e32 v1, 0x6800, v67
	v_lshl_add_u32 v2, s0, 7, v73
	s_add_u32 s0, s1, s18
	ds_write2_b32 v1, v3, v7 offset0:76 offset1:92
	ds_write2_b32 v16, v8, v12 offset0:224 offset1:240
	ds_write2_b32 v0, v9, v13 offset0:100 offset1:116
	ds_write2_b32 v0, v10, v14 offset0:232 offset1:248
	ds_write2_b32 v1, v11, v15 offset0:108 offset1:124
	s_addc_u32 s1, s12, 0
	v_mov_b32_e32 v67, v135
	v_ashrrev_i32_e32 v3, 31, v2
	v_lshl_add_u64 v[0:1], v[64:65], 0, s[18:19]
	v_lshl_add_u64 v[4:5], s[0:1], 0, v[66:67]
	v_lshlrev_b64 v[2:3], 12, v[2:3]
	s_waitcnt lgkmcnt(0)
	s_barrier
	v_lshl_add_u64 v[26:27], v[4:5], 0, v[2:3]
	s_waitcnt vmcnt(0)
	v_mov_b32_e32 v2, v208
	v_mov_b32_e32 v3, v209
	v_mov_b32_e32 v4, v210
	v_mov_b32_e32 v5, v211
	v_mov_b32_e32 v6, v212
	v_mov_b32_e32 v7, v213
	v_mov_b32_e32 v8, v214
	v_mov_b32_e32 v9, v215
	ds_read_b128 v[10:13], v72 offset:59136
	ds_read_b128 v[14:17], v72 offset:59152
	ds_read_b128 v[18:21], v72
	ds_read_b128 v[22:25], v72 offset:16
	v_add_co_u32_e32 v0, vcc, s42, v26
	v_lshl_add_u64 v[28:29], v[26:27], 0, s[60:61]
	s_nop 0
	v_addc_co_u32_e32 v1, vcc, 0, v27, vcc
	v_lshl_add_u64 v[30:31], v[26:27], 0, s[24:25]
	v_lshl_add_u64 v[32:33], v[26:27], 0, s[44:45]
	s_mov_b64 s[0:1], 0x40000
	v_lshl_add_u64 v[34:35], v[26:27], 0, s[0:1]
	s_mov_b64 s[0:1], 0x50000
	v_lshl_add_u64 v[36:37], v[26:27], 0, s[0:1]
	s_mov_b64 s[0:1], 0x60000
	v_lshl_add_u64 v[38:39], v[26:27], 0, s[0:1]
	s_add_i32 s2, s2, s74
	s_mov_b64 s[0:1], 0x70000
	s_cmp_lt_i32 s2, 64
	v_lshl_add_u64 v[40:41], v[26:27], 0, s[0:1]
	s_waitcnt vmcnt(1) lgkmcnt(2)
	v_pk_mul_f32 v[14:15], v[2:3], v[14:15]
	s_waitcnt vmcnt(0) lgkmcnt(1)
	v_pk_mul_f32 v[18:19], v[6:7], v[18:19]
	v_pk_mul_f32 v[20:21], v[8:9], v[20:21]
	global_store_dwordx4 v[26:27], v[18:21], off
	v_pk_mul_f32 v[10:11], v[6:7], v[10:11]
	v_pk_mul_f32 v[12:13], v[8:9], v[12:13]
	s_waitcnt lgkmcnt(0)
	v_pk_mul_f32 v[18:19], v[2:3], v[22:23]
	v_pk_mul_f32 v[20:21], v[4:5], v[24:25]
	global_store_dwordx4 v[26:27], v[18:21], off offset:16
	ds_read_b128 v[18:21], v72 offset:8448
	v_pk_mul_f32 v[16:17], v[4:5], v[16:17]
	s_waitcnt lgkmcnt(0)
	v_pk_mul_f32 v[18:19], v[6:7], v[18:19]
	v_pk_mul_f32 v[20:21], v[8:9], v[20:21]
	global_store_dwordx4 v[0:1], v[18:21], off
	ds_read_b128 v[18:21], v72 offset:8464
	v_add_co_u32_e32 v0, vcc, s66, v26
	s_waitcnt lgkmcnt(0)
	v_pk_mul_f32 v[18:19], v[2:3], v[18:19]
	v_pk_mul_f32 v[20:21], v[4:5], v[20:21]
	global_store_dwordx4 v[28:29], v[18:21], off offset:16
	ds_read_b128 v[18:21], v72 offset:16896
	v_addc_co_u32_e32 v1, vcc, 0, v27, vcc
	s_waitcnt lgkmcnt(0)
	v_pk_mul_f32 v[18:19], v[6:7], v[18:19]
	v_pk_mul_f32 v[20:21], v[8:9], v[20:21]
	global_store_dwordx4 v[0:1], v[18:21], off
	ds_read_b128 v[18:21], v72 offset:16912
	v_add_co_u32_e32 v0, vcc, s13, v26
	s_waitcnt lgkmcnt(0)
	v_pk_mul_f32 v[18:19], v[2:3], v[18:19]
	v_pk_mul_f32 v[20:21], v[4:5], v[20:21]
	global_store_dwordx4 v[30:31], v[18:21], off offset:16
	ds_read_b128 v[18:21], v72 offset:25344
	v_addc_co_u32_e32 v1, vcc, 0, v27, vcc
	s_waitcnt lgkmcnt(0)
	v_pk_mul_f32 v[18:19], v[6:7], v[18:19]
	v_pk_mul_f32 v[20:21], v[8:9], v[20:21]
	global_store_dwordx4 v[0:1], v[18:21], off
	ds_read_b128 v[18:21], v72 offset:25360
	v_add_co_u32_e32 v0, vcc, s3, v26
	s_waitcnt lgkmcnt(0)
	v_pk_mul_f32 v[18:19], v[2:3], v[18:19]
	v_pk_mul_f32 v[20:21], v[4:5], v[20:21]
	global_store_dwordx4 v[32:33], v[18:21], off offset:16
	ds_read_b128 v[18:21], v72 offset:33792
	v_addc_co_u32_e32 v1, vcc, 0, v27, vcc
	s_waitcnt lgkmcnt(0)
	v_pk_mul_f32 v[18:19], v[6:7], v[18:19]
	v_pk_mul_f32 v[20:21], v[8:9], v[20:21]
	global_store_dwordx4 v[0:1], v[18:21], off
	ds_read_b128 v[18:21], v72 offset:33808
	v_add_co_u32_e32 v0, vcc, s69, v26
	s_waitcnt lgkmcnt(0)
	v_pk_mul_f32 v[18:19], v[2:3], v[18:19]
	v_pk_mul_f32 v[20:21], v[4:5], v[20:21]
	global_store_dwordx4 v[34:35], v[18:21], off offset:16
	ds_read_b128 v[18:21], v72 offset:42240
	v_addc_co_u32_e32 v1, vcc, 0, v27, vcc
	s_waitcnt lgkmcnt(0)
	v_pk_mul_f32 v[18:19], v[6:7], v[18:19]
	v_pk_mul_f32 v[20:21], v[8:9], v[20:21]
	global_store_dwordx4 v[0:1], v[18:21], off
	ds_read_b128 v[18:21], v72 offset:42256
	v_add_co_u32_e32 v0, vcc, s49, v26
	s_waitcnt lgkmcnt(0)
	v_pk_mul_f32 v[18:19], v[2:3], v[18:19]
	v_pk_mul_f32 v[20:21], v[4:5], v[20:21]
	global_store_dwordx4 v[36:37], v[18:21], off offset:16
	ds_read_b128 v[18:21], v72 offset:50688
	v_addc_co_u32_e32 v1, vcc, 0, v27, vcc
	s_waitcnt lgkmcnt(0)
	v_pk_mul_f32 v[6:7], v[6:7], v[18:19]
	v_pk_mul_f32 v[8:9], v[8:9], v[20:21]
	global_store_dwordx4 v[0:1], v[6:9], off
	ds_read_b128 v[6:9], v72 offset:50704
	s_waitcnt lgkmcnt(0)
	v_pk_mul_f32 v[0:1], v[2:3], v[6:7]
	v_pk_mul_f32 v[2:3], v[4:5], v[8:9]
	global_store_dwordx4 v[38:39], v[0:3], off offset:16
	s_nop 1
	v_add_co_u32_e32 v0, vcc, 0x70000, v26
	s_nop 1
	v_addc_co_u32_e32 v1, vcc, 0, v27, vcc
	global_store_dwordx4 v[0:1], v[10:13], off
	global_store_dwordx4 v[40:41], v[14:17], off offset:16
	s_cbranch_scc1 .LBB0_665
	v_readlane_b32 s44, v205, 14
	v_readlane_b32 s58, v205, 12
	s_mov_b64 s[22:23], 0x20000
	s_mov_b64 s[24:25], 0x30000
	v_readlane_b32 s45, v205, 15
	v_readlane_b32 s96, v205, 11
	v_readlane_b32 s59, v205, 13
